# st5 fast epilogues write macc directly; the 64-register OUT->macc copy block is skipped (on top of st5 zero64)
# baseline (speedup 1.0000x reference)
.Lbm_join:
	s_cbranch_vccz .LBB0_187

.Lbm_direct:
	s_mov_b64 s[6:7], -1
	s_and_b64 vcc, exec, s[4:5]
	s_cbranch_vccz .Lbm_dtail
	s_and_b64 vcc, exec, s[0:1]
	s_cbranch_vccz .Lbm_d0
	s_barrier

.Lbm_dtail:
	s_andn2_b64 vcc, exec, s[6:7]
	s_mov_b32 s48, s47
	s_mov_b32 s7, s26
	s_mov_b32 s6, s16
	s_mov_b64 s[8:9], s[20:21]
	s_mov_b64 s[10:11], s[18:19]
	s_branch .Lbm_join

.Lbm_fast:
	v_mad_i64_i32 v[248:249], s[12:13], v72, s2, v[74:75]
	global_load_dwordx4 v[208:211], v[248:249], off
	v_or_b32_e32 v250, 16, v72
	v_mad_i64_i32 v[248:249], s[12:13], v250, s2, v[74:75]
	global_load_dwordx4 v[212:215], v[248:249], off
	v_or_b32_e32 v250, 32, v72
	v_mad_i64_i32 v[248:249], s[12:13], v250, s2, v[74:75]
	global_load_dwordx4 v[216:219], v[248:249], off
	v_or_b32_e32 v250, 48, v72
	v_mad_i64_i32 v[248:249], s[12:13], v250, s2, v[74:75]
	global_load_dwordx4 v[220:223], v[248:249], off
	v_add_u32_e32 v250, 0x80, v72
	v_mad_i64_i32 v[248:249], s[12:13], v250, s2, v[74:75]
	global_load_dwordx4 v[224:227], v[248:249], off
	v_add_u32_e32 v250, 0x90, v72
	v_mad_i64_i32 v[248:249], s[12:13], v250, s2, v[74:75]
	global_load_dwordx4 v[228:231], v[248:249], off
	v_add_u32_e32 v250, 0xa0, v72
	v_mad_i64_i32 v[248:249], s[12:13], v250, s2, v[74:75]
	global_load_dwordx4 v[232:235], v[248:249], off
	v_add_u32_e32 v250, 0xb0, v72
	v_mad_i64_i32 v[248:249], s[12:13], v250, s2, v[74:75]
	global_load_dwordx4 v[240:243], v[248:249], off
	s_and_b64 vcc, exec, s[6:7]
	s_cbranch_vccnz .Lbm_fast_mul
	s_waitcnt vmcnt(7)
	v_lshlrev_b32_e32 v186, 16, v208
	v_and_b32_e32 v187, 0xffff0000, v208
	v_lshlrev_b32_e32 v188, 16, v209
	v_and_b32_e32 v189, 0xffff0000, v209
	v_lshlrev_b32_e32 v190, 16, v210
	v_and_b32_e32 v191, 0xffff0000, v210
	v_lshlrev_b32_e32 v192, 16, v211
	v_and_b32_e32 v193, 0xffff0000, v211
	v_mul_f32_e32 v186, 0xbfb8aa3b, v186
	v_mul_f32_e32 v187, 0xbfb8aa3b, v187
	v_mul_f32_e32 v188, 0xbfb8aa3b, v188
	v_mul_f32_e32 v189, 0xbfb8aa3b, v189
	v_mul_f32_e32 v190, 0xbfb8aa3b, v190
	v_mul_f32_e32 v191, 0xbfb8aa3b, v191
	v_mul_f32_e32 v192, 0xbfb8aa3b, v192
	v_mul_f32_e32 v193, 0xbfb8aa3b, v193
	v_exp_f32_e32 v186, v186
	v_exp_f32_e32 v187, v187
	v_exp_f32_e32 v188, v188
	v_exp_f32_e32 v189, v189
	v_exp_f32_e32 v190, v190
	v_exp_f32_e32 v191, v191
	v_exp_f32_e32 v192, v192
	v_exp_f32_e32 v193, v193
	v_add_f32_e32 v186, 1.0, v186
	v_add_f32_e32 v187, 1.0, v187
	v_add_f32_e32 v188, 1.0, v188
	v_add_f32_e32 v189, 1.0, v189
	v_add_f32_e32 v190, 1.0, v190
	v_add_f32_e32 v191, 1.0, v191
	v_add_f32_e32 v192, 1.0, v192
	v_add_f32_e32 v193, 1.0, v193
	v_rcp_f32_e32 v186, v186
	v_rcp_f32_e32 v187, v187
	v_rcp_f32_e32 v188, v188
	v_rcp_f32_e32 v189, v189
	v_rcp_f32_e32 v190, v190
	v_rcp_f32_e32 v191, v191
	v_rcp_f32_e32 v192, v192
	v_rcp_f32_e32 v193, v193
	v_fma_f32 v181, v60, v186, v181
	v_fma_f32 v182, v61, v187, v182
	v_fma_f32 v183, v62, v188, v183
	v_fma_f32 v184, v63, v189, v184
	v_fma_f32 v177, v56, v190, v177
	v_fma_f32 v178, v57, v191, v178
	v_fma_f32 v179, v58, v192, v179
	v_fma_f32 v180, v59, v193, v180
	s_waitcnt vmcnt(6)
	v_lshlrev_b32_e32 v186, 16, v212
	v_and_b32_e32 v187, 0xffff0000, v212
	v_lshlrev_b32_e32 v188, 16, v213
	v_and_b32_e32 v189, 0xffff0000, v213
	v_lshlrev_b32_e32 v190, 16, v214
	v_and_b32_e32 v191, 0xffff0000, v214
	v_lshlrev_b32_e32 v192, 16, v215
	v_and_b32_e32 v193, 0xffff0000, v215
	v_mul_f32_e32 v186, 0xbfb8aa3b, v186
	v_mul_f32_e32 v187, 0xbfb8aa3b, v187
	v_mul_f32_e32 v188, 0xbfb8aa3b, v188
	v_mul_f32_e32 v189, 0xbfb8aa3b, v189
	v_mul_f32_e32 v190, 0xbfb8aa3b, v190
	v_mul_f32_e32 v191, 0xbfb8aa3b, v191
	v_mul_f32_e32 v192, 0xbfb8aa3b, v192
	v_mul_f32_e32 v193, 0xbfb8aa3b, v193
	v_exp_f32_e32 v186, v186
	v_exp_f32_e32 v187, v187
	v_exp_f32_e32 v188, v188
	v_exp_f32_e32 v189, v189
	v_exp_f32_e32 v190, v190
	v_exp_f32_e32 v191, v191
	v_exp_f32_e32 v192, v192
	v_exp_f32_e32 v193, v193
	v_add_f32_e32 v186, 1.0, v186
	v_add_f32_e32 v187, 1.0, v187
	v_add_f32_e32 v188, 1.0, v188
	v_add_f32_e32 v189, 1.0, v189
	v_add_f32_e32 v190, 1.0, v190
	v_add_f32_e32 v191, 1.0, v191
	v_add_f32_e32 v192, 1.0, v192
	v_add_f32_e32 v193, 1.0, v193
	v_rcp_f32_e32 v186, v186
	v_rcp_f32_e32 v187, v187
	v_rcp_f32_e32 v188, v188
	v_rcp_f32_e32 v189, v189
	v_rcp_f32_e32 v190, v190
	v_rcp_f32_e32 v191, v191
	v_rcp_f32_e32 v192, v192
	v_rcp_f32_e32 v193, v193
	v_fma_f32 v173, v52, v186, v173
	v_fma_f32 v174, v53, v187, v174
	v_fma_f32 v175, v54, v188, v175
	v_fma_f32 v176, v55, v189, v176
	v_fma_f32 v169, v48, v190, v169
	v_fma_f32 v170, v49, v191, v170
	v_fma_f32 v171, v50, v192, v171
	v_fma_f32 v172, v51, v193, v172
	s_waitcnt vmcnt(5)
	v_lshlrev_b32_e32 v186, 16, v216
	v_and_b32_e32 v187, 0xffff0000, v216
	v_lshlrev_b32_e32 v188, 16, v217
	v_and_b32_e32 v189, 0xffff0000, v217
	v_lshlrev_b32_e32 v190, 16, v218
	v_and_b32_e32 v191, 0xffff0000, v218
	v_lshlrev_b32_e32 v192, 16, v219
	v_and_b32_e32 v193, 0xffff0000, v219
	v_mul_f32_e32 v186, 0xbfb8aa3b, v186
	v_mul_f32_e32 v187, 0xbfb8aa3b, v187
	v_mul_f32_e32 v188, 0xbfb8aa3b, v188
	v_mul_f32_e32 v189, 0xbfb8aa3b, v189
	v_mul_f32_e32 v190, 0xbfb8aa3b, v190
	v_mul_f32_e32 v191, 0xbfb8aa3b, v191
	v_mul_f32_e32 v192, 0xbfb8aa3b, v192
	v_mul_f32_e32 v193, 0xbfb8aa3b, v193
	v_exp_f32_e32 v186, v186
	v_exp_f32_e32 v187, v187
	v_exp_f32_e32 v188, v188
	v_exp_f32_e32 v189, v189
	v_exp_f32_e32 v190, v190
	v_exp_f32_e32 v191, v191
	v_exp_f32_e32 v192, v192
	v_exp_f32_e32 v193, v193
	v_add_f32_e32 v186, 1.0, v186
	v_add_f32_e32 v187, 1.0, v187
	v_add_f32_e32 v188, 1.0, v188
	v_add_f32_e32 v189, 1.0, v189
	v_add_f32_e32 v190, 1.0, v190
	v_add_f32_e32 v191, 1.0, v191
	v_add_f32_e32 v192, 1.0, v192
	v_add_f32_e32 v193, 1.0, v193
	v_rcp_f32_e32 v186, v186
	v_rcp_f32_e32 v187, v187
	v_rcp_f32_e32 v188, v188
	v_rcp_f32_e32 v189, v189
	v_rcp_f32_e32 v190, v190
	v_rcp_f32_e32 v191, v191
	v_rcp_f32_e32 v192, v192
	v_rcp_f32_e32 v193, v193
	v_fma_f32 v165, v44, v186, v165
	v_fma_f32 v166, v45, v187, v166
	v_fma_f32 v167, v46, v188, v167
	v_fma_f32 v168, v47, v189, v168
	v_fma_f32 v161, v40, v190, v161
	v_fma_f32 v162, v41, v191, v162
	v_fma_f32 v163, v42, v192, v163
	v_fma_f32 v164, v43, v193, v164
	s_waitcnt vmcnt(4)
	v_lshlrev_b32_e32 v186, 16, v220
	v_and_b32_e32 v187, 0xffff0000, v220
	v_lshlrev_b32_e32 v188, 16, v221
	v_and_b32_e32 v189, 0xffff0000, v221
	v_lshlrev_b32_e32 v190, 16, v222
	v_and_b32_e32 v191, 0xffff0000, v222
	v_lshlrev_b32_e32 v192, 16, v223
	v_and_b32_e32 v193, 0xffff0000, v223
	v_mul_f32_e32 v186, 0xbfb8aa3b, v186
	v_mul_f32_e32 v187, 0xbfb8aa3b, v187
	v_mul_f32_e32 v188, 0xbfb8aa3b, v188
	v_mul_f32_e32 v189, 0xbfb8aa3b, v189
	v_mul_f32_e32 v190, 0xbfb8aa3b, v190
	v_mul_f32_e32 v191, 0xbfb8aa3b, v191
	v_mul_f32_e32 v192, 0xbfb8aa3b, v192
	v_mul_f32_e32 v193, 0xbfb8aa3b, v193
	v_exp_f32_e32 v186, v186
	v_exp_f32_e32 v187, v187
	v_exp_f32_e32 v188, v188
	v_exp_f32_e32 v189, v189
	v_exp_f32_e32 v190, v190
	v_exp_f32_e32 v191, v191
	v_exp_f32_e32 v192, v192
	v_exp_f32_e32 v193, v193
	v_add_f32_e32 v186, 1.0, v186
	v_add_f32_e32 v187, 1.0, v187
	v_add_f32_e32 v188, 1.0, v188
	v_add_f32_e32 v189, 1.0, v189
	v_add_f32_e32 v190, 1.0, v190
	v_add_f32_e32 v191, 1.0, v191
	v_add_f32_e32 v192, 1.0, v192
	v_add_f32_e32 v193, 1.0, v193
	v_rcp_f32_e32 v186, v186
	v_rcp_f32_e32 v187, v187
	v_rcp_f32_e32 v188, v188
	v_rcp_f32_e32 v189, v189
	v_rcp_f32_e32 v190, v190
	v_rcp_f32_e32 v191, v191
	v_rcp_f32_e32 v192, v192
	v_rcp_f32_e32 v193, v193
	v_fma_f32 v150, v36, v186, v150
	v_fma_f32 v151, v37, v187, v151
	v_fma_f32 v152, v38, v188, v152
	v_fma_f32 v153, v39, v189, v153
	v_fma_f32 v146, v32, v190, v146
	v_fma_f32 v147, v33, v191, v147
	v_fma_f32 v148, v34, v192, v148
	v_fma_f32 v149, v35, v193, v149
	s_waitcnt vmcnt(3)
	v_lshlrev_b32_e32 v186, 16, v224
	v_and_b32_e32 v187, 0xffff0000, v224
	v_lshlrev_b32_e32 v188, 16, v225
	v_and_b32_e32 v189, 0xffff0000, v225
	v_lshlrev_b32_e32 v190, 16, v226
	v_and_b32_e32 v191, 0xffff0000, v226
	v_lshlrev_b32_e32 v192, 16, v227
	v_and_b32_e32 v193, 0xffff0000, v227
	v_mul_f32_e32 v186, 0xbfb8aa3b, v186
	v_mul_f32_e32 v187, 0xbfb8aa3b, v187
	v_mul_f32_e32 v188, 0xbfb8aa3b, v188
	v_mul_f32_e32 v189, 0xbfb8aa3b, v189
	v_mul_f32_e32 v190, 0xbfb8aa3b, v190
	v_mul_f32_e32 v191, 0xbfb8aa3b, v191
	v_mul_f32_e32 v192, 0xbfb8aa3b, v192
	v_mul_f32_e32 v193, 0xbfb8aa3b, v193
	v_exp_f32_e32 v186, v186
	v_exp_f32_e32 v187, v187
	v_exp_f32_e32 v188, v188
	v_exp_f32_e32 v189, v189
	v_exp_f32_e32 v190, v190
	v_exp_f32_e32 v191, v191
	v_exp_f32_e32 v192, v192
	v_exp_f32_e32 v193, v193
	v_add_f32_e32 v186, 1.0, v186
	v_add_f32_e32 v187, 1.0, v187
	v_add_f32_e32 v188, 1.0, v188
	v_add_f32_e32 v189, 1.0, v189
	v_add_f32_e32 v190, 1.0, v190
	v_add_f32_e32 v191, 1.0, v191
	v_add_f32_e32 v192, 1.0, v192
	v_add_f32_e32 v193, 1.0, v193
	v_rcp_f32_e32 v186, v186
	v_rcp_f32_e32 v187, v187
	v_rcp_f32_e32 v188, v188
	v_rcp_f32_e32 v189, v189
	v_rcp_f32_e32 v190, v190
	v_rcp_f32_e32 v191, v191
	v_rcp_f32_e32 v192, v192
	v_rcp_f32_e32 v193, v193
	v_fma_f32 v140, v28, v186, v140
	v_fma_f32 v141, v29, v187, v141
	v_fma_f32 v142, v30, v188, v142
	v_fma_f32 v143, v31, v189, v143
	v_fma_f32 v136, v24, v190, v136
	v_fma_f32 v137, v25, v191, v137
	v_fma_f32 v138, v26, v192, v138
	v_fma_f32 v139, v27, v193, v139
	s_waitcnt vmcnt(2)
	v_lshlrev_b32_e32 v186, 16, v228
	v_and_b32_e32 v187, 0xffff0000, v228
	v_lshlrev_b32_e32 v188, 16, v229
	v_and_b32_e32 v189, 0xffff0000, v229
	v_lshlrev_b32_e32 v190, 16, v230
	v_and_b32_e32 v191, 0xffff0000, v230
	v_lshlrev_b32_e32 v192, 16, v231
	v_and_b32_e32 v193, 0xffff0000, v231
	v_mul_f32_e32 v186, 0xbfb8aa3b, v186
	v_mul_f32_e32 v187, 0xbfb8aa3b, v187
	v_mul_f32_e32 v188, 0xbfb8aa3b, v188
	v_mul_f32_e32 v189, 0xbfb8aa3b, v189
	v_mul_f32_e32 v190, 0xbfb8aa3b, v190
	v_mul_f32_e32 v191, 0xbfb8aa3b, v191
	v_mul_f32_e32 v192, 0xbfb8aa3b, v192
	v_mul_f32_e32 v193, 0xbfb8aa3b, v193
	v_exp_f32_e32 v186, v186
	v_exp_f32_e32 v187, v187
	v_exp_f32_e32 v188, v188
	v_exp_f32_e32 v189, v189
	v_exp_f32_e32 v190, v190
	v_exp_f32_e32 v191, v191
	v_exp_f32_e32 v192, v192
	v_exp_f32_e32 v193, v193
	v_add_f32_e32 v186, 1.0, v186
	v_add_f32_e32 v187, 1.0, v187
	v_add_f32_e32 v188, 1.0, v188
	v_add_f32_e32 v189, 1.0, v189
	v_add_f32_e32 v190, 1.0, v190
	v_add_f32_e32 v191, 1.0, v191
	v_add_f32_e32 v192, 1.0, v192
	v_add_f32_e32 v193, 1.0, v193
	v_rcp_f32_e32 v186, v186
	v_rcp_f32_e32 v187, v187
	v_rcp_f32_e32 v188, v188
	v_rcp_f32_e32 v189, v189
	v_rcp_f32_e32 v190, v190
	v_rcp_f32_e32 v191, v191
	v_rcp_f32_e32 v192, v192
	v_rcp_f32_e32 v193, v193
	v_fma_f32 v132, v20, v186, v132
	v_fma_f32 v133, v21, v187, v133
	v_fma_f32 v134, v22, v188, v134
	v_fma_f32 v135, v23, v189, v135
	v_fma_f32 v128, v16, v190, v128
	v_fma_f32 v129, v17, v191, v129
	v_fma_f32 v130, v18, v192, v130
	v_fma_f32 v131, v19, v193, v131
	s_waitcnt vmcnt(1)
	v_lshlrev_b32_e32 v186, 16, v232
	v_and_b32_e32 v187, 0xffff0000, v232
	v_lshlrev_b32_e32 v188, 16, v233
	v_and_b32_e32 v189, 0xffff0000, v233
	v_lshlrev_b32_e32 v190, 16, v234
	v_and_b32_e32 v191, 0xffff0000, v234
	v_lshlrev_b32_e32 v192, 16, v235
	v_and_b32_e32 v193, 0xffff0000, v235
	v_mul_f32_e32 v186, 0xbfb8aa3b, v186
	v_mul_f32_e32 v187, 0xbfb8aa3b, v187
	v_mul_f32_e32 v188, 0xbfb8aa3b, v188
	v_mul_f32_e32 v189, 0xbfb8aa3b, v189
	v_mul_f32_e32 v190, 0xbfb8aa3b, v190
	v_mul_f32_e32 v191, 0xbfb8aa3b, v191
	v_mul_f32_e32 v192, 0xbfb8aa3b, v192
	v_mul_f32_e32 v193, 0xbfb8aa3b, v193
	v_exp_f32_e32 v186, v186
	v_exp_f32_e32 v187, v187
	v_exp_f32_e32 v188, v188
	v_exp_f32_e32 v189, v189
	v_exp_f32_e32 v190, v190
	v_exp_f32_e32 v191, v191
	v_exp_f32_e32 v192, v192
	v_exp_f32_e32 v193, v193
	v_add_f32_e32 v186, 1.0, v186
	v_add_f32_e32 v187, 1.0, v187
	v_add_f32_e32 v188, 1.0, v188
	v_add_f32_e32 v189, 1.0, v189
	v_add_f32_e32 v190, 1.0, v190
	v_add_f32_e32 v191, 1.0, v191
	v_add_f32_e32 v192, 1.0, v192
	v_add_f32_e32 v193, 1.0, v193
	v_rcp_f32_e32 v186, v186
	v_rcp_f32_e32 v187, v187
	v_rcp_f32_e32 v188, v188
	v_rcp_f32_e32 v189, v189
	v_rcp_f32_e32 v190, v190
	v_rcp_f32_e32 v191, v191
	v_rcp_f32_e32 v192, v192
	v_rcp_f32_e32 v193, v193
	v_fma_f32 v124, v12, v186, v124
	v_fma_f32 v125, v13, v187, v125
	v_fma_f32 v126, v14, v188, v126
	v_fma_f32 v127, v15, v189, v127
	v_fma_f32 v120, v8, v190, v120
	v_fma_f32 v121, v9, v191, v121
	v_fma_f32 v122, v10, v192, v122
	v_fma_f32 v123, v11, v193, v123
	s_waitcnt vmcnt(0)
	v_lshlrev_b32_e32 v186, 16, v240
	v_and_b32_e32 v187, 0xffff0000, v240
	v_lshlrev_b32_e32 v188, 16, v241
	v_and_b32_e32 v189, 0xffff0000, v241
	v_lshlrev_b32_e32 v190, 16, v242
	v_and_b32_e32 v191, 0xffff0000, v242
	v_lshlrev_b32_e32 v192, 16, v243
	v_and_b32_e32 v193, 0xffff0000, v243
	v_mul_f32_e32 v186, 0xbfb8aa3b, v186
	v_mul_f32_e32 v187, 0xbfb8aa3b, v187
	v_mul_f32_e32 v188, 0xbfb8aa3b, v188
	v_mul_f32_e32 v189, 0xbfb8aa3b, v189
	v_mul_f32_e32 v190, 0xbfb8aa3b, v190
	v_mul_f32_e32 v191, 0xbfb8aa3b, v191
	v_mul_f32_e32 v192, 0xbfb8aa3b, v192
	v_mul_f32_e32 v193, 0xbfb8aa3b, v193
	v_exp_f32_e32 v186, v186
	v_exp_f32_e32 v187, v187
	v_exp_f32_e32 v188, v188
	v_exp_f32_e32 v189, v189
	v_exp_f32_e32 v190, v190
	v_exp_f32_e32 v191, v191
	v_exp_f32_e32 v192, v192
	v_exp_f32_e32 v193, v193
	v_add_f32_e32 v186, 1.0, v186
	v_add_f32_e32 v187, 1.0, v187
	v_add_f32_e32 v188, 1.0, v188
	v_add_f32_e32 v189, 1.0, v189
	v_add_f32_e32 v190, 1.0, v190
	v_add_f32_e32 v191, 1.0, v191
	v_add_f32_e32 v192, 1.0, v192
	v_add_f32_e32 v193, 1.0, v193
	v_rcp_f32_e32 v186, v186
	v_rcp_f32_e32 v187, v187
	v_rcp_f32_e32 v188, v188
	v_rcp_f32_e32 v189, v189
	v_rcp_f32_e32 v190, v190
	v_rcp_f32_e32 v191, v191
	v_rcp_f32_e32 v192, v192
	v_rcp_f32_e32 v193, v193
	v_fma_f32 v116, v4, v186, v116
	v_fma_f32 v117, v5, v187, v117
	v_fma_f32 v118, v6, v188, v118
	v_fma_f32 v119, v7, v189, v119
	v_fma_f32 v112, v0, v190, v112
	v_fma_f32 v113, v1, v191, v113
	v_fma_f32 v114, v2, v192, v114
	v_fma_f32 v115, v3, v193, v115
	s_branch .Lbm_direct
.Lbm_fast_mul:
	s_waitcnt vmcnt(7)
	v_lshlrev_b32_e32 v186, 16, v208
	v_and_b32_e32 v187, 0xffff0000, v208
	v_lshlrev_b32_e32 v188, 16, v209
	v_and_b32_e32 v189, 0xffff0000, v209
	v_lshlrev_b32_e32 v190, 16, v210
	v_and_b32_e32 v191, 0xffff0000, v210
	v_lshlrev_b32_e32 v192, 16, v211
	v_and_b32_e32 v193, 0xffff0000, v211
	v_mul_f32_e32 v186, 0xbfb8aa3b, v186
	v_mul_f32_e32 v187, 0xbfb8aa3b, v187
	v_mul_f32_e32 v188, 0xbfb8aa3b, v188
	v_mul_f32_e32 v189, 0xbfb8aa3b, v189
	v_mul_f32_e32 v190, 0xbfb8aa3b, v190
	v_mul_f32_e32 v191, 0xbfb8aa3b, v191
	v_mul_f32_e32 v192, 0xbfb8aa3b, v192
	v_mul_f32_e32 v193, 0xbfb8aa3b, v193
	v_exp_f32_e32 v186, v186
	v_exp_f32_e32 v187, v187
	v_exp_f32_e32 v188, v188
	v_exp_f32_e32 v189, v189
	v_exp_f32_e32 v190, v190
	v_exp_f32_e32 v191, v191
	v_exp_f32_e32 v192, v192
	v_exp_f32_e32 v193, v193
	v_add_f32_e32 v186, 1.0, v186
	v_add_f32_e32 v187, 1.0, v187
	v_add_f32_e32 v188, 1.0, v188
	v_add_f32_e32 v189, 1.0, v189
	v_add_f32_e32 v190, 1.0, v190
	v_add_f32_e32 v191, 1.0, v191
	v_add_f32_e32 v192, 1.0, v192
	v_add_f32_e32 v193, 1.0, v193
	v_rcp_f32_e32 v186, v186
	v_rcp_f32_e32 v187, v187
	v_rcp_f32_e32 v188, v188
	v_rcp_f32_e32 v189, v189
	v_rcp_f32_e32 v190, v190
	v_rcp_f32_e32 v191, v191
	v_rcp_f32_e32 v192, v192
	v_rcp_f32_e32 v193, v193
	v_mul_f32_e32 v181, v60, v186
	v_mul_f32_e32 v182, v61, v187
	v_mul_f32_e32 v183, v62, v188
	v_mul_f32_e32 v184, v63, v189
	v_mul_f32_e32 v177, v56, v190
	v_mul_f32_e32 v178, v57, v191
	v_mul_f32_e32 v179, v58, v192
	v_mul_f32_e32 v180, v59, v193
	s_waitcnt vmcnt(6)
	v_lshlrev_b32_e32 v186, 16, v212
	v_and_b32_e32 v187, 0xffff0000, v212
	v_lshlrev_b32_e32 v188, 16, v213
	v_and_b32_e32 v189, 0xffff0000, v213
	v_lshlrev_b32_e32 v190, 16, v214
	v_and_b32_e32 v191, 0xffff0000, v214
	v_lshlrev_b32_e32 v192, 16, v215
	v_and_b32_e32 v193, 0xffff0000, v215
	v_mul_f32_e32 v186, 0xbfb8aa3b, v186
	v_mul_f32_e32 v187, 0xbfb8aa3b, v187
	v_mul_f32_e32 v188, 0xbfb8aa3b, v188
	v_mul_f32_e32 v189, 0xbfb8aa3b, v189
	v_mul_f32_e32 v190, 0xbfb8aa3b, v190
	v_mul_f32_e32 v191, 0xbfb8aa3b, v191
	v_mul_f32_e32 v192, 0xbfb8aa3b, v192
	v_mul_f32_e32 v193, 0xbfb8aa3b, v193
	v_exp_f32_e32 v186, v186
	v_exp_f32_e32 v187, v187
	v_exp_f32_e32 v188, v188
	v_exp_f32_e32 v189, v189
	v_exp_f32_e32 v190, v190
	v_exp_f32_e32 v191, v191
	v_exp_f32_e32 v192, v192
	v_exp_f32_e32 v193, v193
	v_add_f32_e32 v186, 1.0, v186
	v_add_f32_e32 v187, 1.0, v187
	v_add_f32_e32 v188, 1.0, v188
	v_add_f32_e32 v189, 1.0, v189
	v_add_f32_e32 v190, 1.0, v190
	v_add_f32_e32 v191, 1.0, v191
	v_add_f32_e32 v192, 1.0, v192
	v_add_f32_e32 v193, 1.0, v193
	v_rcp_f32_e32 v186, v186
	v_rcp_f32_e32 v187, v187
	v_rcp_f32_e32 v188, v188
	v_rcp_f32_e32 v189, v189
	v_rcp_f32_e32 v190, v190
	v_rcp_f32_e32 v191, v191
	v_rcp_f32_e32 v192, v192
	v_rcp_f32_e32 v193, v193
	v_mul_f32_e32 v173, v52, v186
	v_mul_f32_e32 v174, v53, v187
	v_mul_f32_e32 v175, v54, v188
	v_mul_f32_e32 v176, v55, v189
	v_mul_f32_e32 v169, v48, v190
	v_mul_f32_e32 v170, v49, v191
	v_mul_f32_e32 v171, v50, v192
	v_mul_f32_e32 v172, v51, v193
	s_waitcnt vmcnt(5)
	v_lshlrev_b32_e32 v186, 16, v216
	v_and_b32_e32 v187, 0xffff0000, v216
	v_lshlrev_b32_e32 v188, 16, v217
	v_and_b32_e32 v189, 0xffff0000, v217
	v_lshlrev_b32_e32 v190, 16, v218
	v_and_b32_e32 v191, 0xffff0000, v218
	v_lshlrev_b32_e32 v192, 16, v219
	v_and_b32_e32 v193, 0xffff0000, v219
	v_mul_f32_e32 v186, 0xbfb8aa3b, v186
	v_mul_f32_e32 v187, 0xbfb8aa3b, v187
	v_mul_f32_e32 v188, 0xbfb8aa3b, v188
	v_mul_f32_e32 v189, 0xbfb8aa3b, v189
	v_mul_f32_e32 v190, 0xbfb8aa3b, v190
	v_mul_f32_e32 v191, 0xbfb8aa3b, v191
	v_mul_f32_e32 v192, 0xbfb8aa3b, v192
	v_mul_f32_e32 v193, 0xbfb8aa3b, v193
	v_exp_f32_e32 v186, v186
	v_exp_f32_e32 v187, v187
	v_exp_f32_e32 v188, v188
	v_exp_f32_e32 v189, v189
	v_exp_f32_e32 v190, v190
	v_exp_f32_e32 v191, v191
	v_exp_f32_e32 v192, v192
	v_exp_f32_e32 v193, v193
	v_add_f32_e32 v186, 1.0, v186
	v_add_f32_e32 v187, 1.0, v187
	v_add_f32_e32 v188, 1.0, v188
	v_add_f32_e32 v189, 1.0, v189
	v_add_f32_e32 v190, 1.0, v190
	v_add_f32_e32 v191, 1.0, v191
	v_add_f32_e32 v192, 1.0, v192
	v_add_f32_e32 v193, 1.0, v193
	v_rcp_f32_e32 v186, v186
	v_rcp_f32_e32 v187, v187
	v_rcp_f32_e32 v188, v188
	v_rcp_f32_e32 v189, v189
	v_rcp_f32_e32 v190, v190
	v_rcp_f32_e32 v191, v191
	v_rcp_f32_e32 v192, v192
	v_rcp_f32_e32 v193, v193
	v_mul_f32_e32 v165, v44, v186
	v_mul_f32_e32 v166, v45, v187
	v_mul_f32_e32 v167, v46, v188
	v_mul_f32_e32 v168, v47, v189
	v_mul_f32_e32 v161, v40, v190
	v_mul_f32_e32 v162, v41, v191
	v_mul_f32_e32 v163, v42, v192
	v_mul_f32_e32 v164, v43, v193
	s_waitcnt vmcnt(4)
	v_lshlrev_b32_e32 v186, 16, v220
	v_and_b32_e32 v187, 0xffff0000, v220
	v_lshlrev_b32_e32 v188, 16, v221
	v_and_b32_e32 v189, 0xffff0000, v221
	v_lshlrev_b32_e32 v190, 16, v222
	v_and_b32_e32 v191, 0xffff0000, v222
	v_lshlrev_b32_e32 v192, 16, v223
	v_and_b32_e32 v193, 0xffff0000, v223
	v_mul_f32_e32 v186, 0xbfb8aa3b, v186
	v_mul_f32_e32 v187, 0xbfb8aa3b, v187
	v_mul_f32_e32 v188, 0xbfb8aa3b, v188
	v_mul_f32_e32 v189, 0xbfb8aa3b, v189
	v_mul_f32_e32 v190, 0xbfb8aa3b, v190
	v_mul_f32_e32 v191, 0xbfb8aa3b, v191
	v_mul_f32_e32 v192, 0xbfb8aa3b, v192
	v_mul_f32_e32 v193, 0xbfb8aa3b, v193
	v_exp_f32_e32 v186, v186
	v_exp_f32_e32 v187, v187
	v_exp_f32_e32 v188, v188
	v_exp_f32_e32 v189, v189
	v_exp_f32_e32 v190, v190
	v_exp_f32_e32 v191, v191
	v_exp_f32_e32 v192, v192
	v_exp_f32_e32 v193, v193
	v_add_f32_e32 v186, 1.0, v186
	v_add_f32_e32 v187, 1.0, v187
	v_add_f32_e32 v188, 1.0, v188
	v_add_f32_e32 v189, 1.0, v189
	v_add_f32_e32 v190, 1.0, v190
	v_add_f32_e32 v191, 1.0, v191
	v_add_f32_e32 v192, 1.0, v192
	v_add_f32_e32 v193, 1.0, v193
	v_rcp_f32_e32 v186, v186
	v_rcp_f32_e32 v187, v187
	v_rcp_f32_e32 v188, v188
	v_rcp_f32_e32 v189, v189
	v_rcp_f32_e32 v190, v190
	v_rcp_f32_e32 v191, v191
	v_rcp_f32_e32 v192, v192
	v_rcp_f32_e32 v193, v193
	v_mul_f32_e32 v150, v36, v186
	v_mul_f32_e32 v151, v37, v187
	v_mul_f32_e32 v152, v38, v188
	v_mul_f32_e32 v153, v39, v189
	v_mul_f32_e32 v146, v32, v190
	v_mul_f32_e32 v147, v33, v191
	v_mul_f32_e32 v148, v34, v192
	v_mul_f32_e32 v149, v35, v193
	s_waitcnt vmcnt(3)
	v_lshlrev_b32_e32 v186, 16, v224
	v_and_b32_e32 v187, 0xffff0000, v224
	v_lshlrev_b32_e32 v188, 16, v225
	v_and_b32_e32 v189, 0xffff0000, v225
	v_lshlrev_b32_e32 v190, 16, v226
	v_and_b32_e32 v191, 0xffff0000, v226
	v_lshlrev_b32_e32 v192, 16, v227
	v_and_b32_e32 v193, 0xffff0000, v227
	v_mul_f32_e32 v186, 0xbfb8aa3b, v186
	v_mul_f32_e32 v187, 0xbfb8aa3b, v187
	v_mul_f32_e32 v188, 0xbfb8aa3b, v188
	v_mul_f32_e32 v189, 0xbfb8aa3b, v189
	v_mul_f32_e32 v190, 0xbfb8aa3b, v190
	v_mul_f32_e32 v191, 0xbfb8aa3b, v191
	v_mul_f32_e32 v192, 0xbfb8aa3b, v192
	v_mul_f32_e32 v193, 0xbfb8aa3b, v193
	v_exp_f32_e32 v186, v186
	v_exp_f32_e32 v187, v187
	v_exp_f32_e32 v188, v188
	v_exp_f32_e32 v189, v189
	v_exp_f32_e32 v190, v190
	v_exp_f32_e32 v191, v191
	v_exp_f32_e32 v192, v192
	v_exp_f32_e32 v193, v193
	v_add_f32_e32 v186, 1.0, v186
	v_add_f32_e32 v187, 1.0, v187
	v_add_f32_e32 v188, 1.0, v188
	v_add_f32_e32 v189, 1.0, v189
	v_add_f32_e32 v190, 1.0, v190
	v_add_f32_e32 v191, 1.0, v191
	v_add_f32_e32 v192, 1.0, v192
	v_add_f32_e32 v193, 1.0, v193
	v_rcp_f32_e32 v186, v186
	v_rcp_f32_e32 v187, v187
	v_rcp_f32_e32 v188, v188
	v_rcp_f32_e32 v189, v189
	v_rcp_f32_e32 v190, v190
	v_rcp_f32_e32 v191, v191
	v_rcp_f32_e32 v192, v192
	v_rcp_f32_e32 v193, v193
	v_mul_f32_e32 v140, v28, v186
	v_mul_f32_e32 v141, v29, v187
	v_mul_f32_e32 v142, v30, v188
	v_mul_f32_e32 v143, v31, v189
	v_mul_f32_e32 v136, v24, v190
	v_mul_f32_e32 v137, v25, v191
	v_mul_f32_e32 v138, v26, v192
	v_mul_f32_e32 v139, v27, v193
	s_waitcnt vmcnt(2)
	v_lshlrev_b32_e32 v186, 16, v228
	v_and_b32_e32 v187, 0xffff0000, v228
	v_lshlrev_b32_e32 v188, 16, v229
	v_and_b32_e32 v189, 0xffff0000, v229
	v_lshlrev_b32_e32 v190, 16, v230
	v_and_b32_e32 v191, 0xffff0000, v230
	v_lshlrev_b32_e32 v192, 16, v231
	v_and_b32_e32 v193, 0xffff0000, v231
	v_mul_f32_e32 v186, 0xbfb8aa3b, v186
	v_mul_f32_e32 v187, 0xbfb8aa3b, v187
	v_mul_f32_e32 v188, 0xbfb8aa3b, v188
	v_mul_f32_e32 v189, 0xbfb8aa3b, v189
	v_mul_f32_e32 v190, 0xbfb8aa3b, v190
	v_mul_f32_e32 v191, 0xbfb8aa3b, v191
	v_mul_f32_e32 v192, 0xbfb8aa3b, v192
	v_mul_f32_e32 v193, 0xbfb8aa3b, v193
	v_exp_f32_e32 v186, v186
	v_exp_f32_e32 v187, v187
	v_exp_f32_e32 v188, v188
	v_exp_f32_e32 v189, v189
	v_exp_f32_e32 v190, v190
	v_exp_f32_e32 v191, v191
	v_exp_f32_e32 v192, v192
	v_exp_f32_e32 v193, v193
	v_add_f32_e32 v186, 1.0, v186
	v_add_f32_e32 v187, 1.0, v187
	v_add_f32_e32 v188, 1.0, v188
	v_add_f32_e32 v189, 1.0, v189
	v_add_f32_e32 v190, 1.0, v190
	v_add_f32_e32 v191, 1.0, v191
	v_add_f32_e32 v192, 1.0, v192
	v_add_f32_e32 v193, 1.0, v193
	v_rcp_f32_e32 v186, v186
	v_rcp_f32_e32 v187, v187
	v_rcp_f32_e32 v188, v188
	v_rcp_f32_e32 v189, v189
	v_rcp_f32_e32 v190, v190
	v_rcp_f32_e32 v191, v191
	v_rcp_f32_e32 v192, v192
	v_rcp_f32_e32 v193, v193
	v_mul_f32_e32 v132, v20, v186
	v_mul_f32_e32 v133, v21, v187
	v_mul_f32_e32 v134, v22, v188
	v_mul_f32_e32 v135, v23, v189
	v_mul_f32_e32 v128, v16, v190
	v_mul_f32_e32 v129, v17, v191
	v_mul_f32_e32 v130, v18, v192
	v_mul_f32_e32 v131, v19, v193
	s_waitcnt vmcnt(1)
	v_lshlrev_b32_e32 v186, 16, v232
	v_and_b32_e32 v187, 0xffff0000, v232
	v_lshlrev_b32_e32 v188, 16, v233
	v_and_b32_e32 v189, 0xffff0000, v233
	v_lshlrev_b32_e32 v190, 16, v234
	v_and_b32_e32 v191, 0xffff0000, v234
	v_lshlrev_b32_e32 v192, 16, v235
	v_and_b32_e32 v193, 0xffff0000, v235
	v_mul_f32_e32 v186, 0xbfb8aa3b, v186
	v_mul_f32_e32 v187, 0xbfb8aa3b, v187
	v_mul_f32_e32 v188, 0xbfb8aa3b, v188
	v_mul_f32_e32 v189, 0xbfb8aa3b, v189
	v_mul_f32_e32 v190, 0xbfb8aa3b, v190
	v_mul_f32_e32 v191, 0xbfb8aa3b, v191
	v_mul_f32_e32 v192, 0xbfb8aa3b, v192
	v_mul_f32_e32 v193, 0xbfb8aa3b, v193
	v_exp_f32_e32 v186, v186
	v_exp_f32_e32 v187, v187
	v_exp_f32_e32 v188, v188
	v_exp_f32_e32 v189, v189
	v_exp_f32_e32 v190, v190
	v_exp_f32_e32 v191, v191
	v_exp_f32_e32 v192, v192
	v_exp_f32_e32 v193, v193
	v_add_f32_e32 v186, 1.0, v186
	v_add_f32_e32 v187, 1.0, v187
	v_add_f32_e32 v188, 1.0, v188
	v_add_f32_e32 v189, 1.0, v189
	v_add_f32_e32 v190, 1.0, v190
	v_add_f32_e32 v191, 1.0, v191
	v_add_f32_e32 v192, 1.0, v192
	v_add_f32_e32 v193, 1.0, v193
	v_rcp_f32_e32 v186, v186
	v_rcp_f32_e32 v187, v187
	v_rcp_f32_e32 v188, v188
	v_rcp_f32_e32 v189, v189
	v_rcp_f32_e32 v190, v190
	v_rcp_f32_e32 v191, v191
	v_rcp_f32_e32 v192, v192
	v_rcp_f32_e32 v193, v193
	v_mul_f32_e32 v124, v12, v186
	v_mul_f32_e32 v125, v13, v187
	v_mul_f32_e32 v126, v14, v188
	v_mul_f32_e32 v127, v15, v189
	v_mul_f32_e32 v120, v8, v190
	v_mul_f32_e32 v121, v9, v191
	v_mul_f32_e32 v122, v10, v192
	v_mul_f32_e32 v123, v11, v193
	s_waitcnt vmcnt(0)
	v_lshlrev_b32_e32 v186, 16, v240
	v_and_b32_e32 v187, 0xffff0000, v240
	v_lshlrev_b32_e32 v188, 16, v241
	v_and_b32_e32 v189, 0xffff0000, v241
	v_lshlrev_b32_e32 v190, 16, v242
	v_and_b32_e32 v191, 0xffff0000, v242
	v_lshlrev_b32_e32 v192, 16, v243
	v_and_b32_e32 v193, 0xffff0000, v243
	v_mul_f32_e32 v186, 0xbfb8aa3b, v186
	v_mul_f32_e32 v187, 0xbfb8aa3b, v187
	v_mul_f32_e32 v188, 0xbfb8aa3b, v188
	v_mul_f32_e32 v189, 0xbfb8aa3b, v189
	v_mul_f32_e32 v190, 0xbfb8aa3b, v190
	v_mul_f32_e32 v191, 0xbfb8aa3b, v191
	v_mul_f32_e32 v192, 0xbfb8aa3b, v192
	v_mul_f32_e32 v193, 0xbfb8aa3b, v193
	v_exp_f32_e32 v186, v186
	v_exp_f32_e32 v187, v187
	v_exp_f32_e32 v188, v188
	v_exp_f32_e32 v189, v189
	v_exp_f32_e32 v190, v190
	v_exp_f32_e32 v191, v191
	v_exp_f32_e32 v192, v192
	v_exp_f32_e32 v193, v193
	v_add_f32_e32 v186, 1.0, v186
	v_add_f32_e32 v187, 1.0, v187
	v_add_f32_e32 v188, 1.0, v188
	v_add_f32_e32 v189, 1.0, v189
	v_add_f32_e32 v190, 1.0, v190
	v_add_f32_e32 v191, 1.0, v191
	v_add_f32_e32 v192, 1.0, v192
	v_add_f32_e32 v193, 1.0, v193
	v_rcp_f32_e32 v186, v186
	v_rcp_f32_e32 v187, v187
	v_rcp_f32_e32 v188, v188
	v_rcp_f32_e32 v189, v189
	v_rcp_f32_e32 v190, v190
	v_rcp_f32_e32 v191, v191
	v_rcp_f32_e32 v192, v192
	v_rcp_f32_e32 v193, v193
	v_mul_f32_e32 v116, v4, v186
	v_mul_f32_e32 v117, v5, v187
	v_mul_f32_e32 v118, v6, v188
	v_mul_f32_e32 v119, v7, v189
	v_mul_f32_e32 v112, v0, v190
	v_mul_f32_e32 v113, v1, v191
	v_mul_f32_e32 v114, v2, v192
	v_mul_f32_e32 v115, v3, v193
	s_branch .Lbm_direct
